# D1 + V-segment trims: 19-op row-max reduction (was 23), direct branch to exp block instead of v_cmp_gt/vccz double branch, all six attention V bodies
# speedup vs baseline: 1.0184x; 1.0184x over previous
; __device__ __forceinline__ float max3f(float a, float b, float c) { return __builtin_fmaxf(__builtin_fmaxf(a, b), c); }
; __device__ __forceinline__ void rowmax_adjust(f32x16& p0, f32x16& p1, float& m2, f32x16& negm, float& alpha, const bool first) {
;     constexpr float THR2 = THR * 1.4426950408889634f;
;     float pmax = max3f(p0[0], p0[1], p0[2]);
; #pragma unroll
;     for (int r = 3; r < 15; r += 2) pmax = max3f(pmax, p0[r], p0[r + 1]);
;     pmax = max3f(pmax, p0[15], p1[0]);
; #pragma unroll
;     for (int r = 1; r < 15; r += 2) pmax = max3f(pmax, p1[r], p1[r + 1]);
;     pmax = fmaxf(pmax, p1[15]);
;     { auto rr = __builtin_amdgcn_permlane32_swap(__float_as_uint(pmax), __float_as_uint(pmax), false, false);
;       pmax = fmaxf(__uint_as_float(rr[0]), __uint_as_float(rr[1])); }
;     if (!first && __builtin_expect(__all(pmax <= THR2), 1)) { alpha = 1.f; }
;     else {
;         const float delta = first ? pmax : fmaxf(pmax, 0.f);
;         alpha = first ? 1.f : __builtin_amdgcn_exp2f(-delta);
.Ld1_a_nopv:
	s_waitcnt lgkmcnt(0)
	s_mov_b64 s[0:1], s[72:73]
	s_barrier
	v_max3_f32 v168, v96, v97, v98
	v_max3_f32 v168, v168, v99, v100
	v_max3_f32 v168, v168, v101, v102
	v_max3_f32 v168, v168, v103, v104
	v_max3_f32 v168, v168, v105, v106
	v_max3_f32 v168, v168, v107, v108
	v_max3_f32 v168, v168, v109, v110
	v_max3_f32 v168, v168, v111, v80
	v_max3_f32 v168, v168, v81, v82
	v_max3_f32 v168, v168, v83, v84
	v_max3_f32 v168, v168, v85, v86
	v_max3_f32 v168, v168, v87, v88
	v_max3_f32 v168, v168, v89, v90
	v_max3_f32 v168, v168, v91, v92
	v_max3_f32 v168, v168, v93, v94
	v_max_f32_e32 v168, v168, v95
	v_mov_b32_e32 v169, v168
	s_nop 1
	v_permlane32_swap_b32_e32 v168, v169
	v_max_f32_e32 v168, v168, v169
	v_cmp_ge_f32_e32 vcc, s83, v168
	v_mov_b32_e32 v184, 1.0
	s_cmp_lg_u64 s[0:1], 0
	s_cbranch_scc1 .Lvt0_first
	s_cmp_lg_u64 vcc, exec
	s_cbranch_scc1 .Lvt0_rare
	s_branch .LBB0_1162
.Lvt0_first:
	s_mov_b64 s[0:1], -1
	s_branch .LBB0_1156
.Lvt0_rare:
	s_mov_b64 s[0:1], 0
	s_branch .LBB0_1172

; __device__ __forceinline__ float max3f(float a, float b, float c) { return __builtin_fmaxf(__builtin_fmaxf(a, b), c); }
; __device__ __forceinline__ void rowmax_adjust(f32x16& p0, f32x16& p1, float& m2, f32x16& negm, float& alpha, const bool first) {
;     ...
;     float pmax = max3f(p0[0], p0[1], p0[2]);
; #pragma unroll
;     for (int r = 3; r < 15; r += 2) pmax = max3f(pmax, p0[r], p0[r + 1]);
;     pmax = max3f(pmax, p0[15], p1[0]);
; #pragma unroll
;     for (int r = 1; r < 15; r += 2) pmax = max3f(pmax, p1[r], p1[r + 1]);
;     pmax = fmaxf(pmax, p1[15]);
;     { auto rr = __builtin_amdgcn_permlane32_swap(__float_as_uint(pmax), __float_as_uint(pmax), false, false);
;       pmax = fmaxf(__uint_as_float(rr[0]), __uint_as_float(rr[1])); }
;     if (!first && __builtin_expect(__all(pmax <= THR2), 1)) { alpha = 1.f; }
.LBB0_1164:
	s_min_u32 s0, s95, 0x7f
	s_lshl_b32 s0, s0, 16
	s_add_i32 s16, s0, 0x40000
	s_add_u32 s0, s58, s16
	s_addc_u32 s1, s59, 0
	v_lshl_add_u64 v[80:81], s[0:1], 0, v[200:201]
	v_lshl_add_u64 v[82:83], s[0:1], 0, v[202:203]
	global_load_dwordx4 v[132:135], v[80:81], off
	global_load_dwordx4 v[128:131], v[82:83], off
	v_lshl_add_u64 v[80:81], v[204:205], 0, s[16:17]
	global_load_dwordx4 v[136:139], v[80:81], off
	s_waitcnt lgkmcnt(0)
	s_barrier
	s_or_b32 s0, s95, 1
	s_and_b32 s1, s0, 0xff
	s_mulk_i32 s1, 0xab
	s_bfe_u32 s1, s1, 0x70009
	s_mul_i32 s1, s1, 3
	s_sub_i32 s0, s0, s1
	s_and_b32 s0, s0, 0xff
	s_mulk_i32 s0, 0x2400
	v_add_u32_e32 v84, s0, v218
	s_and_b32 s0, s51, 0x8000
	v_add_u32_e32 v187, s0, v217
	ds_read_b128 v[80:83], v84
	ds_read_b128 v[192:195], v84 offset:4608
	ds_read_b128 v[188:191], v84 offset:32
	ds_read_b128 v[196:199], v84 offset:4640
	ds_read_b128 v[220:223], v84 offset:64
	ds_read_b128 v[228:231], v84 offset:4672
	ds_read_b128 v[224:227], v84 offset:96
	ds_read_b128 v[232:235], v84 offset:4704
	ds_read_b64_tr_b16 v[164:165], v187 offset:0
	ds_read_b64_tr_b16 v[166:167], v187 offset:0x800
	ds_read_b64_tr_b16 v[160:161], v187 offset:0x1000
	ds_read_b64_tr_b16 v[162:163], v187 offset:0x1800
	ds_read_b64_tr_b16 v[156:157], v187 offset:0x2000
	ds_read_b64_tr_b16 v[158:159], v187 offset:0x2800
	ds_read_b64_tr_b16 v[152:153], v187 offset:0x3000
	ds_read_b64_tr_b16 v[154:155], v187 offset:0x3800
	s_waitcnt lgkmcnt(15)
	v_mfma_f32_32x32x16_bf16 v[96:111], v[80:83], v[112:115], v[64:79]
	s_waitcnt lgkmcnt(14)
	v_mfma_f32_32x32x16_bf16 v[80:95], v[192:195], v[112:115], v[64:79]
	s_waitcnt lgkmcnt(13)
	v_mfma_f32_32x32x16_bf16 v[96:111], v[188:191], v[116:119], v[96:111]
	s_waitcnt lgkmcnt(12)
	v_mfma_f32_32x32x16_bf16 v[80:95], v[196:199], v[116:119], v[80:95]
	s_waitcnt lgkmcnt(8)
	ds_read_b64_tr_b16 v[188:189], v187 offset:0x200
	ds_read_b64_tr_b16 v[190:191], v187 offset:0xa00
	ds_read_b64_tr_b16 v[192:193], v187 offset:0x1200
	ds_read_b64_tr_b16 v[194:195], v187 offset:0x1a00
	ds_read_b64_tr_b16 v[196:197], v187 offset:0x2200
	ds_read_b64_tr_b16 v[198:199], v187 offset:0x2a00
	ds_read_b64_tr_b16 v[236:237], v187 offset:0x3200
	ds_read_b64_tr_b16 v[238:239], v187 offset:0x3a00
	v_mfma_f32_32x32x16_bf16 v[96:111], v[220:223], v[120:123], v[96:111]
	v_mfma_f32_32x32x16_bf16 v[80:95], v[228:231], v[120:123], v[80:95]
	v_mfma_f32_32x32x16_bf16 v[96:111], v[224:227], v[124:127], v[96:111]
	v_mfma_f32_32x32x16_bf16 v[80:95], v[232:235], v[124:127], v[80:95]
	ds_read_b64_tr_b16 v[220:221], v187 offset:0x600
	ds_read_b64_tr_b16 v[222:223], v187 offset:0xe00
	ds_read_b64_tr_b16 v[224:225], v187 offset:0x1600
	ds_read_b64_tr_b16 v[226:227], v187 offset:0x1e00
	ds_read_b64_tr_b16 v[228:229], v187 offset:0x2600
	ds_read_b64_tr_b16 v[230:231], v187 offset:0x2e00
	ds_read_b64_tr_b16 v[232:233], v187 offset:0x3600
	ds_read_b64_tr_b16 v[234:235], v187 offset:0x3e00
	s_waitcnt lgkmcnt(15)
	v_mfma_f32_32x32x16_bf16 v[48:63], v[180:183], v[164:167], v[48:63]
	v_mfma_f32_32x32x16_bf16 v[48:63], v[176:179], v[160:163], v[48:63]
	v_mfma_f32_32x32x16_bf16 v[48:63], v[172:175], v[156:159], v[48:63]
	v_mfma_f32_32x32x16_bf16 v[48:63], v[168:171], v[152:155], v[48:63]
	ds_read_b64_tr_b16 v[164:165], v187 offset:0x400
	ds_read_b64_tr_b16 v[166:167], v187 offset:0xc00
	ds_read_b64_tr_b16 v[160:161], v187 offset:0x1400
	ds_read_b64_tr_b16 v[162:163], v187 offset:0x1c00
	ds_read_b64_tr_b16 v[156:157], v187 offset:0x2400
	ds_read_b64_tr_b16 v[158:159], v187 offset:0x2c00
	ds_read_b64_tr_b16 v[152:153], v187 offset:0x3400
	ds_read_b64_tr_b16 v[154:155], v187 offset:0x3c00
	s_waitcnt lgkmcnt(15)
	v_mfma_f32_32x32x16_bf16 v[32:47], v[180:183], v[188:191], v[32:47]
	v_mfma_f32_32x32x16_bf16 v[32:47], v[176:179], v[192:195], v[32:47]
	v_mfma_f32_32x32x16_bf16 v[32:47], v[172:175], v[196:199], v[32:47]
	v_mfma_f32_32x32x16_bf16 v[32:47], v[168:171], v[236:239], v[32:47]
	s_waitcnt lgkmcnt(8)
	v_mfma_f32_32x32x16_bf16 v[0:15], v[180:183], v[220:223], v[0:15]
	v_mfma_f32_32x32x16_bf16 v[0:15], v[176:179], v[224:227], v[0:15]
	v_mfma_f32_32x32x16_bf16 v[0:15], v[172:175], v[228:231], v[0:15]
	v_mfma_f32_32x32x16_bf16 v[0:15], v[168:171], v[232:235], v[0:15]
	s_waitcnt lgkmcnt(0)
	v_mfma_f32_32x32x16_bf16 v[16:31], v[180:183], v[164:167], v[16:31]
	v_mfma_f32_32x32x16_bf16 v[16:31], v[176:179], v[160:163], v[16:31]
	v_mfma_f32_32x32x16_bf16 v[16:31], v[172:175], v[156:159], v[16:31]
	v_mfma_f32_32x32x16_bf16 v[16:31], v[168:171], v[152:155], v[16:31]
	s_barrier
	v_max3_f32 v168, v96, v97, v98
	v_max3_f32 v168, v168, v99, v100
	v_max3_f32 v168, v168, v101, v102
	v_max3_f32 v168, v168, v103, v104
	v_max3_f32 v168, v168, v105, v106
	v_max3_f32 v168, v168, v107, v108
	v_max3_f32 v168, v168, v109, v110
	v_max3_f32 v168, v168, v111, v80
	v_max3_f32 v168, v168, v81, v82
	v_max3_f32 v168, v168, v83, v84
	v_max3_f32 v168, v168, v85, v86
	v_max3_f32 v168, v168, v87, v88
	v_max3_f32 v168, v168, v89, v90
	v_max3_f32 v168, v168, v91, v92
	v_max3_f32 v168, v168, v93, v94
	v_max_f32_e32 v168, v168, v95
	v_mov_b32_e32 v169, v168
	s_nop 1
	v_permlane32_swap_b32_e32 v168, v169
	v_max_f32_e32 v168, v168, v169
	v_cmp_ge_f32_e32 vcc, s83, v168
	v_mov_b32_e32 v187, 1.0
	s_cmp_eq_u64 vcc, exec
	s_cbranch_scc1 .LBB0_1169
	s_branch .LBB0_1171

; __device__ __forceinline__ float max3f(float a, float b, float c) { return __builtin_fmaxf(__builtin_fmaxf(a, b), c); }
; __device__ __forceinline__ void rowmax_adjust(f32x16& p0, f32x16& p1, float& m2, f32x16& negm, float& alpha, const bool first) {
;     constexpr float THR2 = THR * 1.4426950408889634f;
;     float pmax = max3f(p0[0], p0[1], p0[2]);
; #pragma unroll
;     for (int r = 3; r < 15; r += 2) pmax = max3f(pmax, p0[r], p0[r + 1]);
;     pmax = max3f(pmax, p0[15], p1[0]);
; #pragma unroll
;     for (int r = 1; r < 15; r += 2) pmax = max3f(pmax, p1[r], p1[r + 1]);
;     pmax = fmaxf(pmax, p1[15]);
;     { auto rr = __builtin_amdgcn_permlane32_swap(__float_as_uint(pmax), __float_as_uint(pmax), false, false);
;       pmax = fmaxf(__uint_as_float(rr[0]), __uint_as_float(rr[1])); }
;     if (!first && __builtin_expect(__all(pmax <= THR2), 1)) { alpha = 1.f; }
.Ld1_b_nopv:
	s_waitcnt lgkmcnt(0)
	s_mov_b64 s[0:1], s[60:61]
	s_barrier
	v_max3_f32 v168, v96, v97, v98
	v_max3_f32 v168, v168, v99, v100
	v_max3_f32 v168, v168, v101, v102
	v_max3_f32 v168, v168, v103, v104
	v_max3_f32 v168, v168, v105, v106
	v_max3_f32 v168, v168, v107, v108
	v_max3_f32 v168, v168, v109, v110
	v_max3_f32 v168, v168, v111, v80
	v_max3_f32 v168, v168, v81, v82
	v_max3_f32 v168, v168, v83, v84
	v_max3_f32 v168, v168, v85, v86
	v_max3_f32 v168, v168, v87, v88
	v_max3_f32 v168, v168, v89, v90
	v_max3_f32 v168, v168, v91, v92
	v_max3_f32 v168, v168, v93, v94
	v_max_f32_e32 v168, v168, v95
	v_mov_b32_e32 v169, v168
	s_nop 1
	v_permlane32_swap_b32_e32 v168, v169
	v_max_f32_e32 v168, v168, v169
	v_cmp_ge_f32_e32 vcc, s83, v168
	v_mov_b32_e32 v184, 1.0
	s_cmp_lg_u64 s[0:1], 0
	s_cbranch_scc1 .Lvt31_first
	s_cmp_lg_u64 vcc, exec
	s_cbranch_scc1 .Lvt31_rare
	s_branch .LBB0_1193

; __device__ __forceinline__ float max3f(float a, float b, float c) { return __builtin_fmaxf(__builtin_fmaxf(a, b), c); }
; __device__ __forceinline__ void rowmax_adjust(f32x16& p0, f32x16& p1, float& m2, f32x16& negm, float& alpha, const bool first) {
;     ...
;     float pmax = max3f(p0[0], p0[1], p0[2]);
; #pragma unroll
;     for (int r = 3; r < 15; r += 2) pmax = max3f(pmax, p0[r], p0[r + 1]);
;     pmax = max3f(pmax, p0[15], p1[0]);
; #pragma unroll
;     for (int r = 1; r < 15; r += 2) pmax = max3f(pmax, p1[r], p1[r + 1]);
;     pmax = fmaxf(pmax, p1[15]);
;     { auto rr = __builtin_amdgcn_permlane32_swap(__float_as_uint(pmax), __float_as_uint(pmax), false, false);
;       pmax = fmaxf(__uint_as_float(rr[0]), __uint_as_float(rr[1])); }
;     if (!first && __builtin_expect(__all(pmax <= THR2), 1)) { alpha = 1.f; }
.LBB0_1195:
	s_min_u32 s0, s64, 0x7f
	s_lshl_b32 s0, s0, 16
	s_add_i32 s16, s0, 0x40000
	s_add_u32 s0, s58, s16
	s_addc_u32 s1, s59, 0
	v_lshl_add_u64 v[80:81], s[0:1], 0, v[200:201]
	v_lshl_add_u64 v[82:83], s[0:1], 0, v[202:203]
	global_load_dwordx4 v[132:135], v[80:81], off
	global_load_dwordx4 v[128:131], v[82:83], off
	v_lshl_add_u64 v[80:81], v[204:205], 0, s[16:17]
	global_load_dwordx4 v[136:139], v[80:81], off
	s_waitcnt lgkmcnt(0)
	s_barrier
	s_or_b32 s0, s64, 1
	s_and_b32 s1, s0, 0xff
	s_mulk_i32 s1, 0xab
	s_bfe_u32 s1, s1, 0x70009
	s_mul_i32 s1, s1, 3
	s_sub_i32 s0, s0, s1
	s_and_b32 s0, s0, 0xff
	s_mulk_i32 s0, 0x2400
	v_add_u32_e32 v84, s0, v218
	s_and_b32 s0, s51, 0x8000
	v_add_u32_e32 v187, s0, v217
	ds_read_b128 v[80:83], v84
	ds_read_b128 v[192:195], v84 offset:4608
	ds_read_b128 v[188:191], v84 offset:32
	ds_read_b128 v[196:199], v84 offset:4640
	ds_read_b128 v[220:223], v84 offset:64
	ds_read_b128 v[228:231], v84 offset:4672
	ds_read_b128 v[224:227], v84 offset:96
	ds_read_b128 v[232:235], v84 offset:4704
	ds_read_b64_tr_b16 v[164:165], v187 offset:0
	ds_read_b64_tr_b16 v[166:167], v187 offset:0x800
	ds_read_b64_tr_b16 v[160:161], v187 offset:0x1000
	ds_read_b64_tr_b16 v[162:163], v187 offset:0x1800
	ds_read_b64_tr_b16 v[156:157], v187 offset:0x2000
	ds_read_b64_tr_b16 v[158:159], v187 offset:0x2800
	ds_read_b64_tr_b16 v[152:153], v187 offset:0x3000
	ds_read_b64_tr_b16 v[154:155], v187 offset:0x3800
	s_waitcnt lgkmcnt(15)
	v_mfma_f32_32x32x16_bf16 v[96:111], v[80:83], v[112:115], v[64:79]
	s_waitcnt lgkmcnt(14)
	v_mfma_f32_32x32x16_bf16 v[80:95], v[192:195], v[112:115], v[64:79]
	s_waitcnt lgkmcnt(13)
	v_mfma_f32_32x32x16_bf16 v[96:111], v[188:191], v[116:119], v[96:111]
	s_waitcnt lgkmcnt(12)
	v_mfma_f32_32x32x16_bf16 v[80:95], v[196:199], v[116:119], v[80:95]
	s_waitcnt lgkmcnt(8)
	ds_read_b64_tr_b16 v[188:189], v187 offset:0x200
	ds_read_b64_tr_b16 v[190:191], v187 offset:0xa00
	ds_read_b64_tr_b16 v[192:193], v187 offset:0x1200
	ds_read_b64_tr_b16 v[194:195], v187 offset:0x1a00
	ds_read_b64_tr_b16 v[196:197], v187 offset:0x2200
	ds_read_b64_tr_b16 v[198:199], v187 offset:0x2a00
	ds_read_b64_tr_b16 v[236:237], v187 offset:0x3200
	ds_read_b64_tr_b16 v[238:239], v187 offset:0x3a00
	v_mfma_f32_32x32x16_bf16 v[96:111], v[220:223], v[120:123], v[96:111]
	v_mfma_f32_32x32x16_bf16 v[80:95], v[228:231], v[120:123], v[80:95]
	v_mfma_f32_32x32x16_bf16 v[96:111], v[224:227], v[124:127], v[96:111]
	v_mfma_f32_32x32x16_bf16 v[80:95], v[232:235], v[124:127], v[80:95]
	ds_read_b64_tr_b16 v[220:221], v187 offset:0x600
	ds_read_b64_tr_b16 v[222:223], v187 offset:0xe00
	ds_read_b64_tr_b16 v[224:225], v187 offset:0x1600
	ds_read_b64_tr_b16 v[226:227], v187 offset:0x1e00
	ds_read_b64_tr_b16 v[228:229], v187 offset:0x2600
	ds_read_b64_tr_b16 v[230:231], v187 offset:0x2e00
	ds_read_b64_tr_b16 v[232:233], v187 offset:0x3600
	ds_read_b64_tr_b16 v[234:235], v187 offset:0x3e00
	s_waitcnt lgkmcnt(15)
	v_mfma_f32_32x32x16_bf16 v[48:63], v[180:183], v[164:167], v[48:63]
	v_mfma_f32_32x32x16_bf16 v[48:63], v[176:179], v[160:163], v[48:63]
	v_mfma_f32_32x32x16_bf16 v[48:63], v[172:175], v[156:159], v[48:63]
	v_mfma_f32_32x32x16_bf16 v[48:63], v[168:171], v[152:155], v[48:63]
	ds_read_b64_tr_b16 v[164:165], v187 offset:0x400
	ds_read_b64_tr_b16 v[166:167], v187 offset:0xc00
	ds_read_b64_tr_b16 v[160:161], v187 offset:0x1400
	ds_read_b64_tr_b16 v[162:163], v187 offset:0x1c00
	ds_read_b64_tr_b16 v[156:157], v187 offset:0x2400
	ds_read_b64_tr_b16 v[158:159], v187 offset:0x2c00
	ds_read_b64_tr_b16 v[152:153], v187 offset:0x3400
	ds_read_b64_tr_b16 v[154:155], v187 offset:0x3c00
	s_waitcnt lgkmcnt(15)
	v_mfma_f32_32x32x16_bf16 v[32:47], v[180:183], v[188:191], v[32:47]
	v_mfma_f32_32x32x16_bf16 v[32:47], v[176:179], v[192:195], v[32:47]
	v_mfma_f32_32x32x16_bf16 v[32:47], v[172:175], v[196:199], v[32:47]
	v_mfma_f32_32x32x16_bf16 v[32:47], v[168:171], v[236:239], v[32:47]
	s_waitcnt lgkmcnt(8)
	v_mfma_f32_32x32x16_bf16 v[0:15], v[180:183], v[220:223], v[0:15]
	v_mfma_f32_32x32x16_bf16 v[0:15], v[176:179], v[224:227], v[0:15]
	v_mfma_f32_32x32x16_bf16 v[0:15], v[172:175], v[228:231], v[0:15]
	v_mfma_f32_32x32x16_bf16 v[0:15], v[168:171], v[232:235], v[0:15]
	s_waitcnt lgkmcnt(0)
	v_mfma_f32_32x32x16_bf16 v[16:31], v[180:183], v[164:167], v[16:31]
	v_mfma_f32_32x32x16_bf16 v[16:31], v[176:179], v[160:163], v[16:31]
	v_mfma_f32_32x32x16_bf16 v[16:31], v[172:175], v[156:159], v[16:31]
	v_mfma_f32_32x32x16_bf16 v[16:31], v[168:171], v[152:155], v[16:31]
	s_barrier
	v_max3_f32 v168, v96, v97, v98
	v_max3_f32 v168, v168, v99, v100
	v_max3_f32 v168, v168, v101, v102
	v_max3_f32 v168, v168, v103, v104
	v_max3_f32 v168, v168, v105, v106
	v_max3_f32 v168, v168, v107, v108
	v_max3_f32 v168, v168, v109, v110
	v_max3_f32 v168, v168, v111, v80
	v_max3_f32 v168, v168, v81, v82
	v_max3_f32 v168, v168, v83, v84
	v_max3_f32 v168, v168, v85, v86
	v_max3_f32 v168, v168, v87, v88
	v_max3_f32 v168, v168, v89, v90
	v_max3_f32 v168, v168, v91, v92
	v_max3_f32 v168, v168, v93, v94
	v_max_f32_e32 v168, v168, v95
	v_mov_b32_e32 v169, v168
	s_nop 1
	v_permlane32_swap_b32_e32 v168, v169
	v_max_f32_e32 v168, v168, v169
	v_cmp_ge_f32_e32 vcc, s83, v168
	v_mov_b32_e32 v187, 1.0
	s_cmp_eq_u64 vcc, exec
	s_cbranch_scc1 .LBB0_1200
	s_branch .LBB0_1202

; __device__ __forceinline__ float max3f(float a, float b, float c) { return __builtin_fmaxf(__builtin_fmaxf(a, b), c); }
; __device__ __forceinline__ void rowmax_adjust(f32x16& p0, f32x16& p1, float& m2, f32x16& negm, float& alpha, const bool first) {
;     ...
;     float pmax = max3f(p0[0], p0[1], p0[2]);
; #pragma unroll
;     for (int r = 3; r < 15; r += 2) pmax = max3f(pmax, p0[r], p0[r + 1]);
;     pmax = max3f(pmax, p0[15], p1[0]);
; #pragma unroll
;     for (int r = 1; r < 15; r += 2) pmax = max3f(pmax, p1[r], p1[r + 1]);
;     pmax = fmaxf(pmax, p1[15]);
;     { auto rr = __builtin_amdgcn_permlane32_swap(__float_as_uint(pmax), __float_as_uint(pmax), false, false);
;       pmax = fmaxf(__uint_as_float(rr[0]), __uint_as_float(rr[1])); }
;     if (!first && __builtin_expect(__all(pmax <= THR2), 1)) { alpha = 1.f; }
.LBB0_1228:
	s_add_i32 s61, s51, -3
	s_mul_i32 s10, s61, 0xab
	s_bfe_u32 s10, s10, 0x70009
	s_mul_i32 s10, s10, 3
	s_sub_i32 s10, s61, s10
	s_and_b32 s10, s10, 0xff
	s_mulk_i32 s10, 0x4400
	v_add_u32_e32 v52, s10, v152
	ds_read_b128 v[48:51], v52 offset:32768
	ds_read_b128 v[158:161], v52 offset:32800
	ds_read_b128 v[162:165], v52 offset:41472
	ds_read_b128 v[166:169], v52 offset:41504
	ds_read_b128 v[170:173], v52 offset:32832
	ds_read_b128 v[174:177], v52 offset:32864
	ds_read_b128 v[178:181], v52 offset:41536
	ds_read_b128 v[182:185], v52 offset:41568
	ds_read_b128 v[186:189], v52 offset:32896
	ds_read_b128 v[190:193], v52 offset:32928
	ds_read_b128 v[194:197], v52 offset:41600
	ds_read_b128 v[202:205], v52 offset:41632
	s_waitcnt lgkmcnt(11)
	v_mfma_f32_32x32x16_bf16 v[64:79], v[48:51], v[80:83], v[32:47]
	s_waitcnt lgkmcnt(9)
	v_mfma_f32_32x32x16_bf16 v[48:63], v[162:165], v[80:83], v[32:47]
	v_mfma_f32_32x32x16_bf16 v[64:79], v[158:161], v[84:87], v[64:79]
	s_waitcnt lgkmcnt(8)
	v_mfma_f32_32x32x16_bf16 v[48:63], v[166:169], v[84:87], v[48:63]
	s_waitcnt lgkmcnt(7)
	v_mfma_f32_32x32x16_bf16 v[64:79], v[170:173], v[88:91], v[64:79]
	s_waitcnt lgkmcnt(5)
	v_mfma_f32_32x32x16_bf16 v[48:63], v[178:181], v[88:91], v[48:63]
	s_waitcnt lgkmcnt(4)
	s_waitcnt lgkmcnt(3)
	s_waitcnt lgkmcnt(1)
	s_waitcnt lgkmcnt(0)
	s_and_b32 s62, s60, 0x6000
	v_add_u32_e32 v198, s62, v155
	ds_read_b64_tr_b16 v[158:159], v198 offset:0
	ds_read_b64_tr_b16 v[160:161], v198 offset:0x400
	ds_read_b64_tr_b16 v[162:163], v198 offset:0x800
	ds_read_b64_tr_b16 v[164:165], v198 offset:0xc00
	ds_read_b64_tr_b16 v[166:167], v198 offset:0x1000
	ds_read_b64_tr_b16 v[168:169], v198 offset:0x1400
	ds_read_b64_tr_b16 v[170:171], v198 offset:0x1800
	ds_read_b64_tr_b16 v[172:173], v198 offset:0x1c00
	ds_read_b64_tr_b16 v[178:179], v198 offset:0x200
	ds_read_b64_tr_b16 v[180:181], v198 offset:0x600
	ds_read_b64_tr_b16 v[210:211], v198 offset:0xa00
	ds_read_b64_tr_b16 v[212:213], v198 offset:0xe00
	ds_read_b64_tr_b16 v[214:215], v198 offset:0x1200
	ds_read_b64_tr_b16 v[216:217], v198 offset:0x1600
	ds_read_b64_tr_b16 v[218:219], v198 offset:0x1a00
	ds_read_b64_tr_b16 v[220:221], v198 offset:0x1e00
	s_nop 0
	v_mfma_f32_32x32x16_bf16 v[64:79], v[174:177], v[92:95], v[64:79]
	v_mfma_f32_32x32x16_bf16 v[48:63], v[182:185], v[92:95], v[48:63]
	v_mfma_f32_32x32x16_bf16 v[64:79], v[186:189], v[96:99], v[64:79]
	v_mfma_f32_32x32x16_bf16 v[48:63], v[194:197], v[96:99], v[48:63]
	v_mfma_f32_32x32x16_bf16 v[64:79], v[190:193], v[100:103], v[64:79]
	v_mfma_f32_32x32x16_bf16 v[48:63], v[202:205], v[100:103], v[48:63]
	s_waitcnt lgkmcnt(0)
	v_mfma_f32_32x32x16_bf16 v[0:15], v[140:143], v[158:161], v[0:15]
	v_mfma_f32_32x32x16_bf16 v[16:31], v[140:143], v[178:181], v[16:31]
	v_mfma_f32_32x32x16_bf16 v[0:15], v[136:139], v[162:165], v[0:15]
	v_mfma_f32_32x32x16_bf16 v[16:31], v[136:139], v[210:213], v[16:31]
	v_mfma_f32_32x32x16_bf16 v[0:15], v[132:135], v[166:169], v[0:15]
	v_mfma_f32_32x32x16_bf16 v[16:31], v[132:135], v[214:217], v[16:31]
	v_mfma_f32_32x32x16_bf16 v[0:15], v[128:131], v[170:173], v[0:15]
	v_mfma_f32_32x32x16_bf16 v[16:31], v[128:131], v[218:221], v[16:31]
	s_barrier
	s_nop 1
	v_max3_f32 v128, v64, v65, v66
	v_max3_f32 v128, v128, v67, v68
	v_max3_f32 v128, v128, v69, v70
	v_max3_f32 v128, v128, v71, v72
	v_max3_f32 v128, v128, v73, v74
	v_max3_f32 v128, v128, v75, v76
	v_max3_f32 v128, v128, v77, v78
	v_max3_f32 v128, v128, v79, v48
	v_max3_f32 v128, v128, v49, v50
	v_max3_f32 v128, v128, v51, v52
	v_max3_f32 v128, v128, v53, v54
	v_max3_f32 v128, v128, v55, v56
	v_max3_f32 v128, v128, v57, v58
	v_max3_f32 v128, v128, v59, v60
	v_max3_f32 v128, v128, v61, v62
	v_max_f32_e32 v128, v128, v63
	v_mov_b32_e32 v129, v128
	s_nop 1
	v_permlane32_swap_b32_e32 v128, v129
	v_max_f32_e32 v128, v128, v129
	v_cmp_ge_f32_e32 vcc, s83, v128
	v_mov_b32_e32 v158, 1.0
	s_cmp_eq_u64 vcc, exec
	s_cbranch_scc1 .LBB0_1233
	s_branch .LBB0_1244

; __device__ __forceinline__ float max3f(float a, float b, float c) { return __builtin_fmaxf(__builtin_fmaxf(a, b), c); }
; __device__ __forceinline__ void rowmax_adjust(f32x16& p0, f32x16& p1, float& m2, f32x16& negm, float& alpha, const bool first) {
;     ...
;     float pmax = max3f(p0[0], p0[1], p0[2]);
; #pragma unroll
;     for (int r = 3; r < 15; r += 2) pmax = max3f(pmax, p0[r], p0[r + 1]);
;     pmax = max3f(pmax, p0[15], p1[0]);
; #pragma unroll
;     for (int r = 1; r < 15; r += 2) pmax = max3f(pmax, p1[r], p1[r + 1]);
;     pmax = fmaxf(pmax, p1[15]);
;     { auto rr = __builtin_amdgcn_permlane32_swap(__float_as_uint(pmax), __float_as_uint(pmax), false, false);
;       pmax = fmaxf(__uint_as_float(rr[0]), __uint_as_float(rr[1])); }
;     if (!first && __builtin_expect(__all(pmax <= THR2), 1)) { alpha = 1.f; }
.LBB0_1236:
	s_min_u32 s10, s61, 0x7f
	s_lshl_b32 s10, s10, 6
	s_add_i32 s16, s10, 0x100
	s_add_i32 s38, s60, 0xffffa000
	s_mul_i32 s10, s16, 0x600
	s_add_u32 s10, s58, s10
	s_addc_u32 s11, s59, 0
	s_lshl_b32 s16, s16, 10
	v_lshl_add_u64 v[48:49], v[148:149], 0, s[16:17]
	v_lshl_add_u64 v[50:51], s[10:11], 0, v[146:147]
	global_load_dwordx4 v[112:115], v[48:49], off
	global_load_dwordx4 v[108:111], v[50:51], off
	v_lshl_add_u64 v[48:49], s[10:11], 0, v[200:201]
	global_load_dwordx4 v[104:107], v[48:49], off
	s_waitcnt lgkmcnt(0)
	s_barrier
	s_or_b32 s10, s61, 1
	s_and_b32 s11, s10, 0xff
	s_mulk_i32 s11, 0xab
	s_bfe_u32 s11, s11, 0x70009
	s_mul_i32 s11, s11, 3
	s_sub_i32 s10, s10, s11
	s_and_b32 s10, s10, 0xff
	s_mulk_i32 s10, 0x4400
	v_add_u32_e32 v52, s10, v152
	ds_read_b128 v[48:51], v52 offset:32768
	ds_read_b128 v[162:165], v52 offset:32800
	ds_read_b128 v[166:169], v52 offset:41472
	ds_read_b128 v[170:173], v52 offset:41504
	ds_read_b128 v[174:177], v52 offset:32832
	ds_read_b128 v[178:181], v52 offset:32864
	ds_read_b128 v[182:185], v52 offset:41536
	ds_read_b128 v[186:189], v52 offset:41568
	ds_read_b128 v[190:193], v52 offset:32896
	ds_read_b128 v[194:197], v52 offset:32928
	ds_read_b128 v[202:205], v52 offset:41600
	ds_read_b128 v[210:213], v52 offset:41632
	s_and_b32 s10, s38, 0x4000
	s_waitcnt lgkmcnt(11)
	v_mfma_f32_32x32x16_bf16 v[64:79], v[48:51], v[80:83], v[32:47]
	s_waitcnt lgkmcnt(9)
	v_mfma_f32_32x32x16_bf16 v[48:63], v[166:169], v[80:83], v[32:47]
	v_mfma_f32_32x32x16_bf16 v[64:79], v[162:165], v[84:87], v[64:79]
	s_waitcnt lgkmcnt(8)
	v_mfma_f32_32x32x16_bf16 v[48:63], v[170:173], v[84:87], v[48:63]
	s_waitcnt lgkmcnt(7)
	v_mfma_f32_32x32x16_bf16 v[64:79], v[174:177], v[88:91], v[64:79]
	s_waitcnt lgkmcnt(5)
	v_mfma_f32_32x32x16_bf16 v[48:63], v[182:185], v[88:91], v[48:63]
	v_add_u32_e32 v161, s10, v155
	s_waitcnt lgkmcnt(4)
	s_waitcnt lgkmcnt(3)
	s_waitcnt lgkmcnt(1)
	s_waitcnt lgkmcnt(0)
	ds_read_b64_tr_b16 v[162:163], v161 offset:0
	ds_read_b64_tr_b16 v[164:165], v161 offset:0x400
	ds_read_b64_tr_b16 v[166:167], v161 offset:0x800
	ds_read_b64_tr_b16 v[168:169], v161 offset:0xc00
	ds_read_b64_tr_b16 v[170:171], v161 offset:0x1000
	ds_read_b64_tr_b16 v[172:173], v161 offset:0x1400
	ds_read_b64_tr_b16 v[174:175], v161 offset:0x1800
	ds_read_b64_tr_b16 v[176:177], v161 offset:0x1c00
	ds_read_b64_tr_b16 v[182:183], v161 offset:0x200
	ds_read_b64_tr_b16 v[184:185], v161 offset:0x600
	ds_read_b64_tr_b16 v[214:215], v161 offset:0xa00
	ds_read_b64_tr_b16 v[216:217], v161 offset:0xe00
	ds_read_b64_tr_b16 v[218:219], v161 offset:0x1200
	ds_read_b64_tr_b16 v[220:221], v161 offset:0x1600
	ds_read_b64_tr_b16 v[222:223], v161 offset:0x1a00
	ds_read_b64_tr_b16 v[224:225], v161 offset:0x1e00
	s_nop 0
	v_mfma_f32_32x32x16_bf16 v[64:79], v[178:181], v[92:95], v[64:79]
	v_mfma_f32_32x32x16_bf16 v[48:63], v[186:189], v[92:95], v[48:63]
	v_mfma_f32_32x32x16_bf16 v[64:79], v[190:193], v[96:99], v[64:79]
	v_mfma_f32_32x32x16_bf16 v[48:63], v[202:205], v[96:99], v[48:63]
	v_mfma_f32_32x32x16_bf16 v[64:79], v[194:197], v[100:103], v[64:79]
	v_mfma_f32_32x32x16_bf16 v[48:63], v[210:213], v[100:103], v[48:63]
	s_waitcnt lgkmcnt(0)
	v_mfma_f32_32x32x16_bf16 v[0:15], v[140:143], v[162:165], v[0:15]
	v_mfma_f32_32x32x16_bf16 v[16:31], v[140:143], v[182:185], v[16:31]
	v_mfma_f32_32x32x16_bf16 v[0:15], v[136:139], v[166:169], v[0:15]
	v_mfma_f32_32x32x16_bf16 v[16:31], v[136:139], v[214:217], v[16:31]
	v_mfma_f32_32x32x16_bf16 v[0:15], v[132:135], v[170:173], v[0:15]
	v_mfma_f32_32x32x16_bf16 v[16:31], v[132:135], v[218:221], v[16:31]
	v_mfma_f32_32x32x16_bf16 v[0:15], v[128:131], v[174:177], v[0:15]
	v_mfma_f32_32x32x16_bf16 v[16:31], v[128:131], v[222:225], v[16:31]
	s_barrier
	s_nop 1
	v_max3_f32 v128, v64, v65, v66
	v_max3_f32 v128, v128, v67, v68
	v_max3_f32 v128, v128, v69, v70
	v_max3_f32 v128, v128, v71, v72
	v_max3_f32 v128, v128, v73, v74
	v_max3_f32 v128, v128, v75, v76
	v_max3_f32 v128, v128, v77, v78
	v_max3_f32 v128, v128, v79, v48
	v_max3_f32 v128, v128, v49, v50
	v_max3_f32 v128, v128, v51, v52
	v_max3_f32 v128, v128, v53, v54
	v_max3_f32 v128, v128, v55, v56
	v_max3_f32 v128, v128, v57, v58
	v_max3_f32 v128, v128, v59, v60
	v_max3_f32 v128, v128, v61, v62
	v_max_f32_e32 v128, v128, v63
	v_mov_b32_e32 v129, v128
	s_nop 1
	v_permlane32_swap_b32_e32 v128, v129
	v_max_f32_e32 v128, v128, v129
	v_cmp_ge_f32_e32 vcc, s83, v128
	v_mov_b32_e32 v161, 1.0
	s_cmp_eq_u64 vcc, exec
	s_cbranch_scc1 .LBB0_1241
	s_branch .LBB0_1245
